# KN3: knorm loop issues the gain load together with the K-row load (one round trip per item instead of two), on top of v065
# baseline (speedup 1.0000x reference)
.LBB0_233:
	v_ashrrev_i32_e32 v12, 12, v1
	v_ashrrev_i32_e32 v13, 31, v12
	v_lshlrev_b32_e32 v44, 8, v12
	v_ashrrev_i32_e32 v45, 31, v44
	v_lshl_add_u64 v[44:45], v[44:45], 2, v[2:3]
	global_load_dwordx4 v[40:43], v[44:45], off
	v_readlane_b32 s0, v250, 61
	v_lshlrev_b64 v[22:23], 21, v[12:13]
	v_readlane_b32 s1, v250, 62
	v_lshlrev_b32_e32 v7, 9, v1
	v_and_b32_e32 v26, 0x1ff800, v7
	v_lshl_add_u64 v[24:25], s[0:1], 0, v[22:23]
	v_mov_b32_e32 v27, v0
	v_lshl_add_u64 v[24:25], v[24:25], 0, v[26:27]
	v_mov_b32_e32 v7, v0
	v_lshl_add_u64 v[24:25], v[24:25], 0, v[6:7]
	v_mov_b32_e32 v9, v0
	v_lshl_add_u64 v[24:25], v[24:25], 0, v[8:9]
	global_load_dwordx2 v[24:25], v[24:25], off
	v_lshrrev_b32_e32 v7, 8, v1
	v_and_b32_e32 v7, 12, v7
	v_or_b32_e32 v9, v7, v4
	s_waitcnt lgkmcnt(0)
	v_lshrrev_b32_e32 v11, 3, v1
	v_lshlrev_b32_e32 v9, 7, v9
	v_and_b32_e32 v11, 0x70, v11
	v_readlane_b32 s0, v250, 63
	v_or3_b32 v9, v9, v11, v20
	v_readlane_b32 s1, v249, 0
	v_lshlrev_b32_e32 v9, 6, v9
	v_bfe_u32 v11, v1, 2, 5
	v_lshl_add_u64 v[22:23], s[0:1], 0, v[22:23]
	v_or3_b32 v30, v9, v19, v11
	v_mov_b32_e32 v31, v0
	v_lshl_add_u64 v[22:23], v[30:31], 4, v[22:23]
	v_mov_b32_e32 v11, v0
	v_lshl_add_u64 v[30:31], v[22:23], 0, v[10:11]
	s_waitcnt vmcnt(0)
	v_lshlrev_b32_e32 v26, 16, v24
	v_and_b32_e32 v27, 0xffff0000, v24
	v_lshlrev_b32_e32 v28, 16, v25
	v_and_b32_e32 v29, 0xffff0000, v25
	v_pk_mul_f32 v[34:35], v[26:27], v[26:27]
	v_pk_mul_f32 v[32:33], v[28:29], v[28:29]
	v_add_f32_e32 v9, v34, v35
	v_add_f32_e32 v9, v9, v32
	v_add_f32_e32 v9, v33, v9
	ds_bpermute_b32 v11, v5, v9
	s_waitcnt lgkmcnt(0)
	v_add_f32_e32 v9, v9, v11
	ds_bpermute_b32 v11, v14, v9
	s_waitcnt lgkmcnt(0)
	v_add_f32_e32 v9, v9, v11
	ds_bpermute_b32 v11, v15, v9
	s_waitcnt lgkmcnt(0)
	v_add_f32_e32 v9, v9, v11
	ds_bpermute_b32 v11, v16, v9
	s_waitcnt lgkmcnt(0)
	v_add_f32_e32 v9, v9, v11
	ds_bpermute_b32 v11, v17, v9
	s_waitcnt lgkmcnt(0)
	v_add_f32_e32 v9, v9, v11
	ds_bpermute_b32 v11, v18, v9
	s_waitcnt lgkmcnt(0)
	v_add_f32_e32 v9, v9, v11
	v_fmamk_f32 v9, v9, 0x3b800000, v221
	v_rsq_f32_e32 v32, v9
	s_nop 0
	v_pk_mul_f32 v[26:27], v[32:33], v[26:27] op_sel_hi:[0,1]
	s_waitcnt vmcnt(0)
	v_pk_mul_f32 v[22:23], v[40:41], v[26:27]
	s_nop 0
	v_cvt_pk_bf16_f32 v22, v22, v23
	v_pk_mul_f32 v[26:27], v[32:33], v[28:29] op_sel_hi:[0,1]
	v_pk_mul_f32 v[24:25], v[42:43], v[26:27]
	v_and_b32_e32 v11, 0xffff0000, v22
	v_cvt_pk_bf16_f32 v23, v24, v25
	v_lshlrev_b32_e32 v9, 16, v22
	v_mul_f32_e32 v11, v11, v11
	v_fmac_f32_e32 v11, v9, v9
	v_lshlrev_b32_e32 v9, 16, v23
	v_fmac_f32_e32 v11, v9, v9
	v_and_b32_e32 v9, 0xffff0000, v23
	v_fmac_f32_e32 v11, v9, v9
	ds_bpermute_b32 v9, v5, v11
	global_store_dwordx2 v[30:31], v[22:23], off
	s_waitcnt lgkmcnt(0)
	v_add_f32_e32 v9, v11, v9
	ds_bpermute_b32 v11, v14, v9
	s_waitcnt lgkmcnt(0)
	v_add_f32_e32 v9, v9, v11
	ds_bpermute_b32 v11, v15, v9
	s_waitcnt lgkmcnt(0)
	v_add_f32_e32 v9, v9, v11
	ds_bpermute_b32 v11, v16, v9
	s_waitcnt lgkmcnt(0)
	v_add_f32_e32 v9, v9, v11
	ds_bpermute_b32 v11, v17, v9
	s_waitcnt lgkmcnt(0)
	v_add_f32_e32 v9, v9, v11
	ds_bpermute_b32 v11, v18, v9
	s_and_saveexec_b64 s[34:35], vcc
	s_cbranch_execz .LBB0_232
	v_lshlrev_b32_e32 v12, 4, v12
	v_readlane_b32 s0, v249, 1
	v_ashrrev_i32_e32 v13, 31, v12
	v_readlane_b32 s1, v249, 2
	v_lshlrev_b32_e32 v22, 2, v7
	v_mov_b32_e32 v23, v0
	v_lshl_add_u64 v[12:13], v[12:13], 2, s[0:1]
	v_lshl_add_u64 v[12:13], v[12:13], 0, v[22:23]
	v_lshlrev_b32_e32 v22, 2, v4
	s_waitcnt lgkmcnt(0)
	v_add_f32_e32 v9, v9, v11
	v_lshl_add_u64 v[12:13], v[12:13], 0, v[22:23]
	global_atomic_umax v[12:13], v9, off
	s_branch .LBB0_232
